# v29 + k-norm: raw-K loads of trips 1..7 hoisted to loop top into private quads with counted vmcnt waits (fixed row-stride shift)
# speedup vs baseline: 1.0064x; 1.0002x over previous
.LBB0_1508:
	s_ashr_i32 s16, s23, 8
	s_ashr_i32 s14, s23, 4
	s_and_b32 s25, s23, 15
	s_ashr_i32 s17, s16, 31
	s_lshl_b64 s[16:17], s[16:17], 12
	s_lshl_b32 s24, s25, 8
	s_lshl_b32 s12, s14, 7
	s_or_b32 s16, s16, s24
	s_and_b32 s12, s12, 0x780
	s_lshl_b32 s12, s12, 1
	v_lshl_add_u64 v[0:1], s[16:17], 0, v[14:15]
	v_lshl_add_u64 v[48:49], v[16:17], 0, s[12:13]
	v_lshlrev_b64 v[0:1], 13, v[0:1]
	v_lshl_add_u64 v[0:1], v[48:49], 0, v[0:1]
	global_load_dwordx4 v[36:39], v[0:1], off
	global_load_dwordx4 v[4:7], v[12:13], off
	s_nop 0
	global_load_dwordx4 v[0:3], v[12:13], off offset:16
	v_lshl_add_u64 v[180:181], s[16:17], 0, v[20:21]
	v_lshlrev_b64 v[180:181], 13, v[180:181]
	v_lshl_add_u64 v[180:181], v[48:49], 0, v[180:181]
	global_load_dwordx4 v[152:155], v[180:181], off
	v_lshl_add_u64 v[180:181], s[16:17], 0, v[22:23]
	v_lshlrev_b64 v[180:181], 13, v[180:181]
	v_lshl_add_u64 v[180:181], v[48:49], 0, v[180:181]
	global_load_dwordx4 v[156:159], v[180:181], off
	v_lshl_add_u64 v[180:181], s[16:17], 0, v[24:25]
	v_lshlrev_b64 v[180:181], 13, v[180:181]
	v_lshl_add_u64 v[180:181], v[48:49], 0, v[180:181]
	global_load_dwordx4 v[160:163], v[180:181], off
	v_lshl_add_u64 v[180:181], s[16:17], 0, v[26:27]
	v_lshlrev_b64 v[180:181], 13, v[180:181]
	v_lshl_add_u64 v[180:181], v[48:49], 0, v[180:181]
	global_load_dwordx4 v[164:167], v[180:181], off
	v_lshl_add_u64 v[180:181], s[16:17], 0, v[28:29]
	v_lshlrev_b64 v[180:181], 13, v[180:181]
	v_lshl_add_u64 v[180:181], v[48:49], 0, v[180:181]
	global_load_dwordx4 v[168:171], v[180:181], off
	v_lshl_add_u64 v[180:181], s[16:17], 0, v[30:31]
	v_lshlrev_b64 v[180:181], 13, v[180:181]
	v_lshl_add_u64 v[180:181], v[48:49], 0, v[180:181]
	global_load_dwordx4 v[172:175], v[180:181], off
	v_lshl_add_u64 v[180:181], s[16:17], 0, v[32:33]
	v_lshlrev_b64 v[180:181], 13, v[180:181]
	v_lshl_add_u64 v[180:181], v[48:49], 0, v[180:181]
	global_load_dwordx4 v[176:179], v[180:181], off
	s_ashr_i32 s15, s14, 31
	s_lshl_b64 s[18:19], s[14:15], 12
	s_or_b32 s18, s18, s24
	s_waitcnt vmcnt(9)
	v_lshlrev_b32_e32 v44, 16, v36
	v_and_b32_e32 v45, 0xffff0000, v36
	v_lshlrev_b32_e32 v40, 16, v39
	v_and_b32_e32 v41, 0xffff0000, v39
	v_lshlrev_b32_e32 v42, 16, v38
	v_and_b32_e32 v43, 0xffff0000, v38
	v_lshlrev_b32_e32 v38, 16, v37
	v_and_b32_e32 v39, 0xffff0000, v37
	v_pk_mul_f32 v[52:53], v[44:45], v[44:45]
	v_pk_mul_f32 v[50:51], v[38:39], v[38:39]
	v_add_f32_e32 v10, v52, v53
	v_add_f32_e32 v10, v50, v10
	v_pk_mul_f32 v[46:47], v[42:43], v[42:43]
	v_add_f32_e32 v10, v51, v10
	v_add_f32_e32 v10, v46, v10
	v_pk_mul_f32 v[36:37], v[40:41], v[40:41]
	v_add_f32_e32 v10, v47, v10
	v_add_f32_e32 v10, v36, v10
	v_add_f32_e32 v10, v37, v10
	ds_bpermute_b32 v35, v95, v10
	v_lshl_add_u64 v[36:37], s[18:19], 0, v[14:15]
	v_lshlrev_b64 v[36:37], 8, v[36:37]
	v_lshl_add_u64 v[54:55], v[18:19], 0, v[36:37]
	v_lshl_add_u64 v[46:47], s[16:17], 0, v[20:21]
	s_waitcnt lgkmcnt(0)
	v_add_f32_e32 v10, v10, v35
	ds_bpermute_b32 v35, v96, v10
	v_lshlrev_b64 v[46:47], 13, v[46:47]
	v_lshl_add_u64 v[46:47], v[48:49], 0, v[46:47]
	s_waitcnt lgkmcnt(0)
	v_add_f32_e32 v10, v10, v35
	ds_bpermute_b32 v35, v97, v10
	s_waitcnt lgkmcnt(0)
	v_add_f32_e32 v10, v10, v35
	ds_bpermute_b32 v35, v98, v10
	s_waitcnt lgkmcnt(0)
	v_add_f32_e32 v10, v10, v35
	v_fmamk_f32 v10, v10, 0x3c000000, v103
	v_mul_f32_e32 v35, 0x4b800000, v10
	v_cmp_gt_f32_e32 vcc, s6, v10
	s_nop 1
	v_cndmask_b32_e32 v10, v10, v35, vcc
	v_rsq_f32_e32 v10, v10
	s_nop 0
	v_mul_f32_e32 v35, 0x45800000, v10
	v_cndmask_b32_e32 v10, v10, v35, vcc
	v_pk_mul_f32 v[36:37], v[10:11], v[44:45] op_sel_hi:[0,1]
	v_pk_mul_f32 v[38:39], v[10:11], v[38:39] op_sel_hi:[0,1]
	v_pk_mul_f32 v[42:43], v[10:11], v[42:43] op_sel_hi:[0,1]
	v_pk_mul_f32 v[50:51], v[10:11], v[40:41] op_sel_hi:[0,1]
	s_waitcnt vmcnt(8)
	v_pk_mul_f32 v[44:45], v[4:5], v[36:37]
	v_pk_mul_f32 v[40:41], v[6:7], v[38:39]
	s_waitcnt vmcnt(7)
	v_pk_mul_f32 v[38:39], v[0:1], v[42:43]
	v_pk_mul_f32 v[36:37], v[2:3], v[50:51]
	v_cvt_pk_bf16_f32 v50, v44, v45
	v_cvt_pk_bf16_f32 v51, v40, v41
	v_cvt_pk_bf16_f32 v52, v38, v39
	v_cvt_pk_bf16_f32 v53, v36, v37
	global_store_dwordx4 v[54:55], v[50:53], off
	v_add_f32_e32 v44, 0, v44
	s_waitcnt vmcnt(6)
	v_lshlrev_b32_e32 v54, 16, v152
	v_and_b32_e32 v55, 0xffff0000, v152
	v_lshlrev_b32_e32 v42, 16, v155
	v_and_b32_e32 v43, 0xffff0000, v155
	v_lshlrev_b32_e32 v46, 16, v154
	v_and_b32_e32 v47, 0xffff0000, v154
	v_lshlrev_b32_e32 v52, 16, v153
	v_and_b32_e32 v53, 0xffff0000, v153
	v_pk_mul_f32 v[60:61], v[54:55], v[54:55]
	v_pk_mul_f32 v[58:59], v[52:53], v[52:53]
	v_add_f32_e32 v10, v60, v61
	v_add_f32_e32 v10, v58, v10
	v_pk_mul_f32 v[56:57], v[46:47], v[46:47]
	v_add_f32_e32 v10, v59, v10
	v_add_f32_e32 v10, v56, v10
	v_pk_mul_f32 v[50:51], v[42:43], v[42:43]
	v_add_f32_e32 v10, v57, v10
	v_add_f32_e32 v10, v50, v10
	v_add_f32_e32 v10, v51, v10
	ds_bpermute_b32 v35, v95, v10
	v_lshl_add_u64 v[50:51], s[18:19], 0, v[20:21]
	v_lshlrev_b64 v[50:51], 8, v[50:51]
	v_lshl_add_u64 v[56:57], s[16:17], 0, v[22:23]
	v_lshl_add_u64 v[60:61], v[18:19], 0, v[50:51]
	s_waitcnt lgkmcnt(0)
	v_add_f32_e32 v10, v10, v35
	ds_bpermute_b32 v35, v96, v10
	v_lshlrev_b64 v[56:57], 13, v[56:57]
	v_lshl_add_u64 v[62:63], v[48:49], 0, v[56:57]
	s_waitcnt lgkmcnt(0)
	v_add_f32_e32 v10, v10, v35
	ds_bpermute_b32 v35, v97, v10
	s_waitcnt lgkmcnt(0)
	v_add_f32_e32 v10, v10, v35
	ds_bpermute_b32 v35, v98, v10
	s_waitcnt lgkmcnt(0)
	v_add_f32_e32 v10, v10, v35
	v_fmamk_f32 v10, v10, 0x3c000000, v103
	v_mul_f32_e32 v35, 0x4b800000, v10
	v_cmp_gt_f32_e32 vcc, s6, v10
	s_nop 1
	v_cndmask_b32_e32 v10, v10, v35, vcc
	v_rsq_f32_e32 v10, v10
	s_nop 0
	v_mul_f32_e32 v35, 0x45800000, v10
	v_cndmask_b32_e32 v10, v10, v35, vcc
	v_pk_mul_f32 v[50:51], v[10:11], v[54:55] op_sel_hi:[0,1]
	v_pk_mul_f32 v[52:53], v[10:11], v[52:53] op_sel_hi:[0,1]
	v_pk_mul_f32 v[46:47], v[10:11], v[46:47] op_sel_hi:[0,1]
	v_pk_mul_f32 v[42:43], v[10:11], v[42:43] op_sel_hi:[0,1]
	v_pk_mul_f32 v[54:55], v[4:5], v[50:51]
	v_pk_mul_f32 v[50:51], v[6:7], v[52:53]
	v_pk_mul_f32 v[46:47], v[0:1], v[46:47]
	v_pk_mul_f32 v[42:43], v[2:3], v[42:43]
	v_cvt_pk_bf16_f32 v56, v54, v55
	v_cvt_pk_bf16_f32 v57, v50, v51
	v_cvt_pk_bf16_f32 v58, v46, v47
	v_cvt_pk_bf16_f32 v59, v42, v43
	global_store_dwordx4 v[60:61], v[56:59], off
	v_add_f32_e32 v44, v44, v54
	s_waitcnt vmcnt(5)
	v_lshlrev_b32_e32 v62, 16, v156
	v_and_b32_e32 v63, 0xffff0000, v156
	v_lshlrev_b32_e32 v52, 16, v159
	v_and_b32_e32 v53, 0xffff0000, v159
	v_lshlrev_b32_e32 v60, 16, v158
	v_and_b32_e32 v61, 0xffff0000, v158
	v_lshlrev_b32_e32 v58, 16, v157
	v_and_b32_e32 v59, 0xffff0000, v157
	v_pk_mul_f32 v[68:69], v[62:63], v[62:63]
	v_pk_mul_f32 v[66:67], v[58:59], v[58:59]
	v_add_f32_e32 v10, v68, v69
	v_add_f32_e32 v10, v66, v10
	v_pk_mul_f32 v[64:65], v[60:61], v[60:61]
	v_add_f32_e32 v10, v67, v10
	v_add_f32_e32 v10, v64, v10
	v_pk_mul_f32 v[56:57], v[52:53], v[52:53]
	v_add_f32_e32 v10, v65, v10
	v_add_f32_e32 v10, v56, v10
	v_add_f32_e32 v10, v57, v10
	ds_bpermute_b32 v35, v95, v10
	v_lshl_add_u64 v[56:57], s[18:19], 0, v[22:23]
	v_lshlrev_b64 v[56:57], 8, v[56:57]
	v_lshl_add_u64 v[64:65], s[16:17], 0, v[24:25]
	v_lshl_add_u64 v[68:69], v[18:19], 0, v[56:57]
	s_waitcnt lgkmcnt(0)
	v_add_f32_e32 v10, v10, v35
	ds_bpermute_b32 v35, v96, v10
	v_lshlrev_b64 v[64:65], 13, v[64:65]
	v_lshl_add_u64 v[70:71], v[48:49], 0, v[64:65]
	s_waitcnt lgkmcnt(0)
	v_add_f32_e32 v10, v10, v35
	ds_bpermute_b32 v35, v97, v10
	s_waitcnt lgkmcnt(0)
	v_add_f32_e32 v10, v10, v35
	ds_bpermute_b32 v35, v98, v10
	s_waitcnt lgkmcnt(0)
	v_add_f32_e32 v10, v10, v35
	v_fmamk_f32 v10, v10, 0x3c000000, v103
	v_mul_f32_e32 v35, 0x4b800000, v10
	v_cmp_gt_f32_e32 vcc, s6, v10
	s_nop 1
	v_cndmask_b32_e32 v10, v10, v35, vcc
	v_rsq_f32_e32 v10, v10
	s_nop 0
	v_mul_f32_e32 v35, 0x45800000, v10
	v_cndmask_b32_e32 v10, v10, v35, vcc
	v_pk_mul_f32 v[56:57], v[10:11], v[62:63] op_sel_hi:[0,1]
	v_pk_mul_f32 v[58:59], v[10:11], v[58:59] op_sel_hi:[0,1]
	v_pk_mul_f32 v[60:61], v[10:11], v[60:61] op_sel_hi:[0,1]
	v_pk_mul_f32 v[52:53], v[10:11], v[52:53] op_sel_hi:[0,1]
	v_pk_mul_f32 v[62:63], v[4:5], v[56:57]
	v_pk_mul_f32 v[58:59], v[6:7], v[58:59]
	v_pk_mul_f32 v[56:57], v[0:1], v[60:61]
	v_pk_mul_f32 v[52:53], v[2:3], v[52:53]
	v_cvt_pk_bf16_f32 v64, v62, v63
	v_cvt_pk_bf16_f32 v65, v58, v59
	v_cvt_pk_bf16_f32 v66, v56, v57
	v_cvt_pk_bf16_f32 v67, v52, v53
	global_store_dwordx4 v[68:69], v[64:67], off
	v_add_f32_e32 v44, v44, v62
	s_waitcnt vmcnt(4)
	v_lshlrev_b32_e32 v70, 16, v160
	v_and_b32_e32 v71, 0xffff0000, v160
	v_lshlrev_b32_e32 v60, 16, v163
	v_and_b32_e32 v61, 0xffff0000, v163
	v_lshlrev_b32_e32 v68, 16, v162
	v_and_b32_e32 v69, 0xffff0000, v162
	v_lshlrev_b32_e32 v66, 16, v161
	v_and_b32_e32 v67, 0xffff0000, v161
	v_pk_mul_f32 v[76:77], v[70:71], v[70:71]
	v_pk_mul_f32 v[74:75], v[66:67], v[66:67]
	v_add_f32_e32 v10, v76, v77
	v_add_f32_e32 v10, v74, v10
	v_pk_mul_f32 v[72:73], v[68:69], v[68:69]
	v_add_f32_e32 v10, v75, v10
	v_add_f32_e32 v10, v72, v10
	v_pk_mul_f32 v[64:65], v[60:61], v[60:61]
	v_add_f32_e32 v10, v73, v10
	v_add_f32_e32 v10, v64, v10
	v_add_f32_e32 v10, v65, v10
	ds_bpermute_b32 v35, v95, v10
	v_lshl_add_u64 v[64:65], s[18:19], 0, v[24:25]
	v_lshlrev_b64 v[64:65], 8, v[64:65]
	v_lshl_add_u64 v[72:73], s[16:17], 0, v[26:27]
	v_lshl_add_u64 v[76:77], v[18:19], 0, v[64:65]
	s_waitcnt lgkmcnt(0)
	v_add_f32_e32 v10, v10, v35
	ds_bpermute_b32 v35, v96, v10
	v_lshlrev_b64 v[72:73], 13, v[72:73]
	v_lshl_add_u64 v[78:79], v[48:49], 0, v[72:73]
	s_waitcnt lgkmcnt(0)
	v_add_f32_e32 v10, v10, v35
	ds_bpermute_b32 v35, v97, v10
	s_waitcnt lgkmcnt(0)
	v_add_f32_e32 v10, v10, v35
	ds_bpermute_b32 v35, v98, v10
	s_waitcnt lgkmcnt(0)
	v_add_f32_e32 v10, v10, v35
	v_fmamk_f32 v10, v10, 0x3c000000, v103
	v_mul_f32_e32 v35, 0x4b800000, v10
	v_cmp_gt_f32_e32 vcc, s6, v10
	s_nop 1
	v_cndmask_b32_e32 v10, v10, v35, vcc
	v_rsq_f32_e32 v10, v10
	s_nop 0
	v_mul_f32_e32 v35, 0x45800000, v10
	v_cndmask_b32_e32 v10, v10, v35, vcc
	v_pk_mul_f32 v[64:65], v[10:11], v[70:71] op_sel_hi:[0,1]
	v_pk_mul_f32 v[66:67], v[10:11], v[66:67] op_sel_hi:[0,1]
	v_pk_mul_f32 v[68:69], v[10:11], v[68:69] op_sel_hi:[0,1]
	v_pk_mul_f32 v[60:61], v[10:11], v[60:61] op_sel_hi:[0,1]
	v_pk_mul_f32 v[70:71], v[4:5], v[64:65]
	v_pk_mul_f32 v[66:67], v[6:7], v[66:67]
	v_pk_mul_f32 v[64:65], v[0:1], v[68:69]
	v_pk_mul_f32 v[60:61], v[2:3], v[60:61]
	v_cvt_pk_bf16_f32 v72, v70, v71
	v_cvt_pk_bf16_f32 v73, v66, v67
	v_cvt_pk_bf16_f32 v74, v64, v65
	v_cvt_pk_bf16_f32 v75, v60, v61
	global_store_dwordx4 v[76:77], v[72:75], off
	v_add_f32_e32 v44, v44, v70
	s_waitcnt vmcnt(3)
	v_lshlrev_b32_e32 v78, 16, v164
	v_and_b32_e32 v79, 0xffff0000, v164
	v_lshlrev_b32_e32 v68, 16, v167
	v_and_b32_e32 v69, 0xffff0000, v167
	v_lshlrev_b32_e32 v76, 16, v166
	v_and_b32_e32 v77, 0xffff0000, v166
	v_lshlrev_b32_e32 v74, 16, v165
	v_and_b32_e32 v75, 0xffff0000, v165
	v_pk_mul_f32 v[84:85], v[78:79], v[78:79]
	v_pk_mul_f32 v[82:83], v[74:75], v[74:75]
	v_add_f32_e32 v10, v84, v85
	v_add_f32_e32 v10, v82, v10
	v_pk_mul_f32 v[80:81], v[76:77], v[76:77]
	v_add_f32_e32 v10, v83, v10
	v_add_f32_e32 v10, v80, v10
	v_pk_mul_f32 v[72:73], v[68:69], v[68:69]
	v_add_f32_e32 v10, v81, v10
	v_add_f32_e32 v10, v72, v10
	v_add_f32_e32 v10, v73, v10
	ds_bpermute_b32 v35, v95, v10
	v_lshl_add_u64 v[72:73], s[18:19], 0, v[26:27]
	v_lshlrev_b64 v[72:73], 8, v[72:73]
	v_lshl_add_u64 v[80:81], s[16:17], 0, v[28:29]
	v_lshl_add_u64 v[84:85], v[18:19], 0, v[72:73]
	s_waitcnt lgkmcnt(0)
	v_add_f32_e32 v10, v10, v35
	ds_bpermute_b32 v35, v96, v10
	v_lshlrev_b64 v[80:81], 13, v[80:81]
	v_lshl_add_u64 v[86:87], v[48:49], 0, v[80:81]
	s_waitcnt lgkmcnt(0)
	v_add_f32_e32 v10, v10, v35
	ds_bpermute_b32 v35, v97, v10
	s_waitcnt lgkmcnt(0)
	v_add_f32_e32 v10, v10, v35
	ds_bpermute_b32 v35, v98, v10
	s_waitcnt lgkmcnt(0)
	v_add_f32_e32 v10, v10, v35
	v_fmamk_f32 v10, v10, 0x3c000000, v103
	v_mul_f32_e32 v35, 0x4b800000, v10
	v_cmp_gt_f32_e32 vcc, s6, v10
	s_nop 1
	v_cndmask_b32_e32 v10, v10, v35, vcc
	v_rsq_f32_e32 v10, v10
	s_nop 0
	v_mul_f32_e32 v35, 0x45800000, v10
	v_cndmask_b32_e32 v10, v10, v35, vcc
	v_pk_mul_f32 v[72:73], v[10:11], v[78:79] op_sel_hi:[0,1]
	v_pk_mul_f32 v[74:75], v[10:11], v[74:75] op_sel_hi:[0,1]
	v_pk_mul_f32 v[76:77], v[10:11], v[76:77] op_sel_hi:[0,1]
	v_pk_mul_f32 v[68:69], v[10:11], v[68:69] op_sel_hi:[0,1]
	v_pk_mul_f32 v[78:79], v[4:5], v[72:73]
	v_pk_mul_f32 v[74:75], v[6:7], v[74:75]
	v_pk_mul_f32 v[72:73], v[0:1], v[76:77]
	v_pk_mul_f32 v[68:69], v[2:3], v[68:69]
	v_cvt_pk_bf16_f32 v80, v78, v79
	v_cvt_pk_bf16_f32 v81, v74, v75
	v_cvt_pk_bf16_f32 v82, v72, v73
	v_cvt_pk_bf16_f32 v83, v68, v69
	global_store_dwordx4 v[84:85], v[80:83], off
	s_waitcnt vmcnt(2)
	v_lshlrev_b32_e32 v86, 16, v168
	v_and_b32_e32 v87, 0xffff0000, v168
	v_lshlrev_b32_e32 v76, 16, v171
	v_and_b32_e32 v77, 0xffff0000, v171
	v_lshlrev_b32_e32 v84, 16, v170
	v_and_b32_e32 v85, 0xffff0000, v170
	v_lshlrev_b32_e32 v82, 16, v169
	v_and_b32_e32 v83, 0xffff0000, v169
	v_pk_mul_f32 v[92:93], v[86:87], v[86:87]
	v_pk_mul_f32 v[90:91], v[82:83], v[82:83]
	v_add_f32_e32 v10, v92, v93
	v_add_f32_e32 v10, v90, v10
	v_pk_mul_f32 v[88:89], v[84:85], v[84:85]
	v_add_f32_e32 v10, v91, v10
	v_add_f32_e32 v10, v88, v10
	v_pk_mul_f32 v[80:81], v[76:77], v[76:77]
	v_add_f32_e32 v10, v89, v10
	v_add_f32_e32 v10, v80, v10
	v_add_f32_e32 v10, v81, v10
	ds_bpermute_b32 v35, v95, v10
	v_lshl_add_u64 v[80:81], s[18:19], 0, v[28:29]
	v_lshlrev_b64 v[80:81], 8, v[80:81]
	v_lshl_add_u64 v[88:89], s[16:17], 0, v[30:31]
	v_lshl_add_u64 v[90:91], v[18:19], 0, v[80:81]
	s_waitcnt lgkmcnt(0)
	v_add_f32_e32 v10, v10, v35
	ds_bpermute_b32 v35, v96, v10
	v_lshlrev_b64 v[88:89], 13, v[88:89]
	v_lshl_add_u64 v[92:93], v[48:49], 0, v[88:89]
	s_waitcnt lgkmcnt(0)
	v_add_f32_e32 v10, v10, v35
	ds_bpermute_b32 v35, v97, v10
	s_waitcnt lgkmcnt(0)
	v_add_f32_e32 v10, v10, v35
	ds_bpermute_b32 v35, v98, v10
	s_waitcnt lgkmcnt(0)
	v_add_f32_e32 v10, v10, v35
	v_fmamk_f32 v10, v10, 0x3c000000, v103
	v_mul_f32_e32 v35, 0x4b800000, v10
	v_cmp_gt_f32_e32 vcc, s6, v10
	s_nop 1
	v_cndmask_b32_e32 v10, v10, v35, vcc
	v_rsq_f32_e32 v10, v10
	s_nop 0
	v_mul_f32_e32 v35, 0x45800000, v10
	v_cndmask_b32_e32 v10, v10, v35, vcc
	v_pk_mul_f32 v[80:81], v[10:11], v[86:87] op_sel_hi:[0,1]
	v_pk_mul_f32 v[82:83], v[10:11], v[82:83] op_sel_hi:[0,1]
	v_pk_mul_f32 v[86:87], v[10:11], v[84:85] op_sel_hi:[0,1]
	v_pk_mul_f32 v[76:77], v[10:11], v[76:77] op_sel_hi:[0,1]
	v_pk_mul_f32 v[84:85], v[4:5], v[80:81]
	v_pk_mul_f32 v[82:83], v[6:7], v[82:83]
	v_pk_mul_f32 v[80:81], v[0:1], v[86:87]
	v_pk_mul_f32 v[76:77], v[2:3], v[76:77]
	v_cvt_pk_bf16_f32 v86, v84, v85
	v_cvt_pk_bf16_f32 v87, v82, v83
	v_cvt_pk_bf16_f32 v88, v80, v81
	v_cvt_pk_bf16_f32 v89, v76, v77
	global_store_dwordx4 v[90:91], v[86:89], off
	s_waitcnt vmcnt(1)
	v_lshlrev_b32_e32 v106, 16, v172
	v_and_b32_e32 v107, 0xffff0000, v172
	v_lshlrev_b32_e32 v90, 16, v175
	v_and_b32_e32 v91, 0xffff0000, v175
	v_lshlrev_b32_e32 v92, 16, v174
	v_and_b32_e32 v93, 0xffff0000, v174
	v_lshlrev_b32_e32 v88, 16, v173
	v_and_b32_e32 v89, 0xffff0000, v173
	v_pk_mul_f32 v[112:113], v[106:107], v[106:107]
	v_pk_mul_f32 v[110:111], v[88:89], v[88:89]
	v_add_f32_e32 v10, v112, v113
	v_add_f32_e32 v10, v110, v10
	v_pk_mul_f32 v[108:109], v[92:93], v[92:93]
	v_add_f32_e32 v10, v111, v10
	v_add_f32_e32 v10, v108, v10
	v_pk_mul_f32 v[86:87], v[90:91], v[90:91]
	v_add_f32_e32 v10, v109, v10
	v_add_f32_e32 v10, v86, v10
	v_add_f32_e32 v10, v87, v10
	ds_bpermute_b32 v35, v95, v10
	v_lshl_add_u64 v[86:87], s[18:19], 0, v[30:31]
	v_lshl_add_u64 v[108:109], s[16:17], 0, v[32:33]
	v_lshlrev_b64 v[86:87], 8, v[86:87]
	v_lshlrev_b64 v[108:109], 13, v[108:109]
	s_waitcnt lgkmcnt(0)
	v_add_f32_e32 v10, v10, v35
	ds_bpermute_b32 v35, v96, v10
	v_lshl_add_u64 v[110:111], v[18:19], 0, v[86:87]
	v_lshl_add_u64 v[112:113], v[48:49], 0, v[108:109]
	s_waitcnt lgkmcnt(0)
	v_add_f32_e32 v10, v10, v35
	ds_bpermute_b32 v35, v97, v10
	s_waitcnt lgkmcnt(0)
	v_add_f32_e32 v10, v10, v35
	ds_bpermute_b32 v35, v98, v10
	s_waitcnt lgkmcnt(0)
	v_add_f32_e32 v10, v10, v35
	v_fmamk_f32 v10, v10, 0x3c000000, v103
	v_mul_f32_e32 v35, 0x4b800000, v10
	v_cmp_gt_f32_e32 vcc, s6, v10
	s_nop 1
	v_cndmask_b32_e32 v10, v10, v35, vcc
	v_rsq_f32_e32 v10, v10
	s_nop 0
	v_mul_f32_e32 v35, 0x45800000, v10
	v_cndmask_b32_e32 v10, v10, v35, vcc
	v_pk_mul_f32 v[48:49], v[10:11], v[106:107] op_sel_hi:[0,1]
	v_pk_mul_f32 v[86:87], v[10:11], v[88:89] op_sel_hi:[0,1]
	v_pk_mul_f32 v[92:93], v[10:11], v[92:93] op_sel_hi:[0,1]
	v_pk_mul_f32 v[106:107], v[10:11], v[90:91] op_sel_hi:[0,1]
	v_pk_mul_f32 v[90:91], v[4:5], v[48:49]
	v_pk_mul_f32 v[88:89], v[6:7], v[86:87]
	v_pk_mul_f32 v[86:87], v[0:1], v[92:93]
	v_pk_mul_f32 v[48:49], v[2:3], v[106:107]
	v_cvt_pk_bf16_f32 v106, v90, v91
	v_cvt_pk_bf16_f32 v107, v88, v89
	v_cvt_pk_bf16_f32 v108, v86, v87
	v_cvt_pk_bf16_f32 v109, v48, v49
	global_store_dwordx4 v[110:111], v[106:109], off
	s_waitcnt vmcnt(0)
	v_lshlrev_b32_e32 v112, 16, v176
	v_and_b32_e32 v113, 0xffff0000, v176
	v_lshlrev_b32_e32 v92, 16, v179
	v_and_b32_e32 v93, 0xffff0000, v179
	v_lshlrev_b32_e32 v110, 16, v178
	v_and_b32_e32 v111, 0xffff0000, v178
	v_lshlrev_b32_e32 v108, 16, v177
	v_and_b32_e32 v109, 0xffff0000, v177
	v_pk_mul_f32 v[118:119], v[112:113], v[112:113]
	v_pk_mul_f32 v[116:117], v[108:109], v[108:109]
	v_add_f32_e32 v10, v118, v119
	v_add_f32_e32 v10, v116, v10
	v_pk_mul_f32 v[114:115], v[110:111], v[110:111]
	v_add_f32_e32 v10, v117, v10
	v_add_f32_e32 v10, v114, v10
	v_pk_mul_f32 v[106:107], v[92:93], v[92:93]
	v_add_f32_e32 v10, v115, v10
	v_add_f32_e32 v10, v106, v10
	v_add_f32_e32 v10, v107, v10
	ds_bpermute_b32 v35, v95, v10
	s_waitcnt lgkmcnt(0)
	v_add_f32_e32 v10, v10, v35
	ds_bpermute_b32 v35, v96, v10
	s_waitcnt lgkmcnt(0)
	v_add_f32_e32 v10, v10, v35
	ds_bpermute_b32 v35, v97, v10
	s_waitcnt lgkmcnt(0)
	v_add_f32_e32 v10, v10, v35
	ds_bpermute_b32 v35, v98, v10
	s_waitcnt lgkmcnt(0)
	v_add_f32_e32 v10, v10, v35
	v_fmamk_f32 v10, v10, 0x3c000000, v103
	v_mul_f32_e32 v35, 0x4b800000, v10
	v_cmp_gt_f32_e32 vcc, s6, v10
	s_nop 1
	v_cndmask_b32_e32 v10, v10, v35, vcc
	v_rsq_f32_e32 v10, v10
	v_add_f32_e32 v35, v44, v78
	v_add_f32_e32 v35, v35, v84
	v_add_f32_e32 v35, v35, v90
	v_mul_f32_e32 v44, 0x45800000, v10
	v_cndmask_b32_e32 v10, v10, v44, vcc
	v_pk_mul_f32 v[106:107], v[10:11], v[112:113] op_sel_hi:[0,1]
	v_pk_mul_f32 v[112:113], v[10:11], v[92:93] op_sel_hi:[0,1]
	v_pk_mul_f32 v[92:93], v[4:5], v[106:107]
	v_pk_mul_f32 v[108:109], v[10:11], v[108:109] op_sel_hi:[0,1]
	v_pk_mul_f32 v[110:111], v[10:11], v[110:111] op_sel_hi:[0,1]
	v_add_f32_e32 v10, v35, v92
	v_pk_mul_f32 v[4:5], v[0:1], v[110:111]
	v_pk_mul_f32 v[0:1], v[2:3], v[112:113]
	ds_bpermute_b32 v2, v99, v10
	v_lshl_add_u64 v[110:111], s[18:19], 0, v[32:33]
	v_pk_mul_f32 v[6:7], v[6:7], v[108:109]
	v_lshlrev_b64 v[110:111], 8, v[110:111]
	v_cvt_pk_bf16_f32 v106, v92, v93
	s_waitcnt lgkmcnt(0)
	v_add_f32_e32 v2, v10, v2
	ds_bpermute_b32 v3, v100, v2
	v_cvt_pk_bf16_f32 v107, v6, v7
	v_cvt_pk_bf16_f32 v108, v4, v5
	v_cvt_pk_bf16_f32 v109, v0, v1
	v_lshl_add_u64 v[110:111], v[18:19], 0, v[110:111]
	global_store_dwordx4 v[110:111], v[106:109], off
	s_and_saveexec_b64 s[18:19], s[0:1]
	s_cbranch_execz .LBB0_1510
	s_waitcnt lgkmcnt(0)
	v_add_f32_e32 v2, v2, v3
	ds_write_b32 v104, v2
